# NSA edge tiles: skip 32-key halves that are masked for every query (above diagonal / below window)
# speedup vs baseline: 1.0081x; 1.0081x over previous
.LBB0_293:
	v_cndmask_b32_e64 v61, v167, v206, s[38:39]
	v_sub_f32_e32 v62, v48, v61
	v_exp_f32_e32 v62, v62
	v_sub_f32_e32 v63, v2, v61
	v_exp_f32_e32 v63, v63
	v_cmp_lt_f32_e32 vcc, s68, v48
	v_sub_f32_e32 v66, v49, v61
	v_exp_f32_e32 v66, v66
	v_cndmask_b32_e32 v62, 0, v62, vcc
	v_cmp_lt_f32_e32 vcc, s68, v2
	v_add_f32_e32 v48, 0, v62
	s_xor_b64 s[6:7], s[4:5], -1
	v_cndmask_b32_e32 v2, 0, v63, vcc
	v_cmp_lt_f32_e32 vcc, s68, v49
	v_sub_f32_e32 v49, v50, v61
	v_exp_f32_e32 v49, v49
	v_cndmask_b32_e32 v63, 0, v66, vcc
	v_sub_f32_e32 v66, v51, v61
	v_cmp_lt_f32_e32 vcc, s68, v50
	v_exp_f32_e32 v66, v66
	v_sub_f32_e32 v50, v54, v61
	v_cndmask_b32_e32 v67, 0, v49, vcc
	v_sub_f32_e32 v49, v52, v61
	v_exp_f32_e32 v49, v49
	v_cmp_lt_f32_e32 vcc, s68, v51
	v_exp_f32_e32 v50, v50
	v_add_f32_e32 v48, v2, v48
	v_cndmask_b32_e32 v66, 0, v66, vcc
	v_cmp_lt_f32_e32 vcc, s68, v52
	v_add_f32_e32 v48, v63, v48
	v_add_f32_e32 v48, v67, v48
	v_cndmask_b32_e32 v68, 0, v49, vcc
	v_sub_f32_e32 v49, v53, v61
	v_exp_f32_e32 v49, v49
	v_cmp_lt_f32_e32 vcc, s68, v54
	v_add_f32_e32 v48, v66, v48
	v_add_f32_e32 v48, v68, v48
	v_cndmask_b32_e32 v69, 0, v50, vcc
	v_sub_f32_e32 v50, v55, v61
	v_cmp_lt_f32_e32 vcc, s68, v53
	v_exp_f32_e32 v50, v50
	v_add_f32_e32 v48, v69, v48
	v_cndmask_b32_e32 v70, 0, v49, vcc
	v_sub_f32_e32 v49, v56, v61
	v_exp_f32_e32 v49, v49
	v_cmp_lt_f32_e32 vcc, s68, v55
	v_add_f32_e32 v48, v70, v48
	v_sub_f32_e32 v52, v60, v61
	v_cndmask_b32_e32 v71, 0, v50, vcc
	v_cmp_lt_f32_e32 vcc, s68, v56
	v_add_f32_e32 v48, v71, v48
	v_sub_f32_e32 v50, v57, v61
	v_cndmask_b32_e32 v56, 0, v49, vcc
	v_exp_f32_e32 v50, v50
	v_add_f32_e32 v72, v56, v48
	v_sub_f32_e32 v48, v64, v61
	v_exp_f32_e32 v48, v48
	v_cmp_lt_f32_e32 vcc, s68, v57
	v_sub_f32_e32 v49, v65, v61
	v_exp_f32_e32 v49, v49
	v_cndmask_b32_e32 v73, 0, v50, vcc
	v_cmp_lt_f32_e32 vcc, s68, v64
	v_exp_f32_e32 v77, v52
	v_cvt_pk_bf16_f32 v52, v62, v2
	v_cndmask_b32_e32 v74, 0, v48, vcc
	v_sub_f32_e32 v48, v59, v61
	v_exp_f32_e32 v57, v48
	v_add_u32_e32 v48, s16, v156
	v_lshl_add_u32 v64, v48, 1, v172
	v_cmp_lt_f32_e32 vcc, s68, v65
	v_add_u32_e32 v76, 0x2000, v64
	v_add_u32_e32 v2, 0x3000, v64
	v_cndmask_b32_e32 v75, 0, v49, vcc
	ds_read2_b64 v[48:51], v76 offset0:128 offset1:130
	v_cvt_pk_bf16_f32 v53, v63, v67
	ds_read2_b64 v[62:65], v2 offset0:192 offset1:194
	v_cvt_pk_bf16_f32 v54, v66, v68
	v_cvt_pk_bf16_f32 v55, v69, v70
	v_cmp_lt_f32_e32 vcc, s68, v59
	s_mov_b32 s16, 32
	s_waitcnt lgkmcnt(1)
	v_mfma_f32_32x32x16_bf16 v[32:47], v[48:51], v[52:55], v[32:47]
	v_sub_f32_e32 v48, v58, v61
	v_cndmask_b32_e32 v66, 0, v57, vcc
	v_exp_f32_e32 v57, v48
	v_cmp_lt_f32_e32 vcc, s68, v60
	ds_read2_b64 v[48:51], v76 offset0:132 offset1:134
	s_mov_b64 s[4:5], 0
	v_cndmask_b32_e32 v60, 0, v77, vcc
	v_cmp_lt_f32_e32 vcc, s68, v58
	s_waitcnt lgkmcnt(1)
	v_mfma_f32_32x32x16_bf16 v[16:31], v[62:65], v[52:55], v[16:31]
	v_cvt_pk_bf16_f32 v52, v71, v56
	v_cndmask_b32_e32 v61, 0, v57, vcc
	ds_read2_b64 v[56:59], v2 offset0:196 offset1:198
	v_cvt_pk_bf16_f32 v53, v73, v74
	v_cvt_pk_bf16_f32 v54, v75, v66
	v_cvt_pk_bf16_f32 v55, v60, v61
	v_add_f32_e32 v2, v73, v72
	v_add_f32_e32 v2, v74, v2
	s_waitcnt lgkmcnt(1)
	v_mfma_f32_32x32x16_bf16 v[32:47], v[48:51], v[52:55], v[32:47]
	v_add_f32_e32 v2, v75, v2
	v_add_f32_e32 v2, v66, v2
	v_add_f32_e32 v2, v60, v2
	v_add_f32_e32 v2, v61, v2
	v_fmac_f32_e32 v2, v169, v0
	s_and_b64 vcc, exec, s[6:7]
	s_waitcnt lgkmcnt(0)
	v_mfma_f32_32x32x16_bf16 v[16:31], v[56:59], v[52:55], v[16:31]
	s_cbranch_vccnz .LBB0_295
	v_mov_b32_e32 v169, v2
	s_add_i32 s6, s15, 1
	s_cmp_gt_i32 s6, s8
	s_cbranch_scc1 .LBB0_296
	s_branch .LBB0_291

.LBB0_301:
	s_add_i32 s13, s12, 1
	s_min_i32 s4, s13, s10
	s_lshl_b32 s4, s4, 6
	s_ashr_i32 s5, s4, 31
	s_lshl_b64 s[6:7], s[4:5], 7
	s_lshl_b64 s[4:5], s[4:5], 1
	v_lshl_add_u64 v[14:15], v[190:191], 0, s[6:7]
	v_lshl_add_u64 v[10:11], v[164:165], 0, s[4:5]
	global_load_dwordx4 v[6:9], v[14:15], off offset:-2048
	s_nop 0
	global_load_dwordx4 v[2:5], v[14:15], off offset:2048
	v_lshl_add_u64 v[14:15], v[166:167], 0, s[4:5]
	global_load_dwordx4 v[10:13], v[10:11], off
	s_nop 0
	global_load_dwordx4 v[112:115], v[14:15], off
	s_sub_i32 s4, s12, s11
	s_lshl_b32 s6, s12, 6
	s_and_b32 s14, s4, 1
	s_or_b32 s4, s6, 63
	s_cmp_le_i32 s4, s8
	s_cselect_b64 s[4:5], -1, 0
	s_cmp_gt_i32 s6, s9
	s_mul_i32 s7, s14, 0x4800
	s_cselect_b64 s[16:17], -1, 0
	s_and_b64 s[16:17], s[4:5], s[16:17]
	v_or_b32_e32 v14, s7, v129
	s_mov_b64 s[4:5], -1
	s_and_b64 vcc, exec, s[16:17]
	v_add_u32_e32 v15, v14, v161
	s_cbranch_vccnz .LBB0_307
	v_mov_b64_e32 v[78:79], v[30:31]
	v_mov_b64_e32 v[62:63], v[46:47]
	v_or_b32_e32 v171, s6, v131
	s_mov_b32 s6, 0
	v_mov_b64_e32 v[76:77], v[28:29]
	v_mov_b64_e32 v[74:75], v[26:27]
	v_mov_b64_e32 v[72:73], v[24:25]
	v_mov_b64_e32 v[70:71], v[22:23]
	v_mov_b64_e32 v[68:69], v[20:21]
	v_mov_b64_e32 v[66:67], v[18:19]
	v_mov_b64_e32 v[64:65], v[16:17]
	v_mov_b64_e32 v[60:61], v[44:45]
	v_mov_b64_e32 v[58:59], v[42:43]
	v_mov_b64_e32 v[56:57], v[40:41]
	v_mov_b64_e32 v[54:55], v[38:39]
	v_mov_b64_e32 v[52:53], v[36:37]
	v_mov_b64_e32 v[50:51], v[34:35]
	v_mov_b64_e32 v[48:49], v[32:33]
	v_mov_b32_e32 v172, v169
	v_mov_b32_e32 v170, v168
	s_lshl_b32 s7, s12, 6
	s_add_i32 s7, s7, 62
	s_cmp_le_i32 s7, s9
	s_cselect_b32 s6, 32, 0
	s_cselect_b64 s[4:5], 0, -1

.LBB0_305:
	v_sub_f32_e32 v91, v80, v170
	v_exp_f32_e32 v91, v91
	v_sub_f32_e32 v92, v81, v170
	v_exp_f32_e32 v92, v92
	v_cmp_lt_f32_e32 vcc, s68, v80
	v_sub_f32_e32 v93, v82, v170
	v_exp_f32_e32 v93, v93
	v_cndmask_b32_e32 v91, 0, v91, vcc
	v_cmp_lt_f32_e32 vcc, s68, v81
	v_sub_f32_e32 v81, v83, v170
	v_exp_f32_e32 v81, v81
	v_cndmask_b32_e32 v92, 0, v92, vcc
	v_cmp_lt_f32_e32 vcc, s68, v82
	v_sub_f32_e32 v82, v84, v170
	v_exp_f32_e32 v82, v82
	v_cndmask_b32_e32 v93, 0, v93, vcc
	v_cmp_lt_f32_e32 vcc, s68, v83
	v_add_f32_e32 v80, 0, v91
	v_add_f32_e32 v80, v92, v80
	v_cndmask_b32_e32 v94, 0, v81, vcc
	v_sub_f32_e32 v81, v173, v170
	v_exp_f32_e32 v81, v81
	v_cmp_lt_f32_e32 vcc, s68, v84
	v_add_f32_e32 v80, v93, v80
	v_add_f32_e32 v80, v94, v80
	v_cndmask_b32_e32 v84, 0, v82, vcc
	v_sub_f32_e32 v82, v177, v170
	v_cmp_lt_f32_e32 vcc, s68, v173
	v_exp_f32_e32 v82, v82
	v_add_f32_e32 v80, v84, v80
	v_cndmask_b32_e32 v95, 0, v81, vcc
	v_sub_f32_e32 v81, v175, v170
	v_exp_f32_e32 v81, v81
	v_cmp_lt_f32_e32 vcc, s68, v177
	v_add_f32_e32 v80, v95, v80
	s_xor_b64 s[4:5], s[4:5], -1
	v_cndmask_b32_e32 v173, 0, v82, vcc
	v_sub_f32_e32 v82, v176, v170
	v_cmp_lt_f32_e32 vcc, s68, v175
	v_exp_f32_e32 v82, v82
	v_add_f32_e32 v80, v173, v80
	v_cndmask_b32_e32 v175, 0, v81, vcc
	v_sub_f32_e32 v81, v89, v170
	v_exp_f32_e32 v81, v81
	v_cmp_lt_f32_e32 vcc, s68, v176
	v_add_f32_e32 v80, v175, v80
	s_nop 0
	v_cndmask_b32_e32 v176, 0, v82, vcc
	v_cmp_lt_f32_e32 vcc, s68, v89
	v_add_f32_e32 v80, v176, v80
	v_sub_f32_e32 v82, v174, v170
	v_cndmask_b32_e32 v177, 0, v81, vcc
	v_exp_f32_e32 v82, v82
	v_add_f32_e32 v178, v177, v80
	v_sub_f32_e32 v80, v88, v170
	v_exp_f32_e32 v80, v80
	v_cmp_lt_f32_e32 vcc, s68, v174
	v_sub_f32_e32 v81, v90, v170
	v_exp_f32_e32 v81, v81
	v_cndmask_b32_e32 v174, 0, v82, vcc
	v_cmp_lt_f32_e32 vcc, s68, v88
	v_sub_f32_e32 v88, v87, v170
	v_exp_f32_e32 v213, v88
	v_cndmask_b32_e32 v179, 0, v80, vcc
	v_sub_f32_e32 v80, v85, v170
	v_exp_f32_e32 v181, v80
	v_add_u32_e32 v80, s6, v159
	v_lshl_add_u32 v182, v80, 1, v15
	v_cmp_lt_f32_e32 vcc, s68, v90
	v_add_u32_e32 v183, 0x2000, v182
	v_cvt_pk_bf16_f32 v88, v91, v92
	v_cndmask_b32_e32 v180, 0, v81, vcc
	ds_read2_b64 v[80:83], v183 offset0:128 offset1:130
	v_cvt_pk_bf16_f32 v91, v173, v175
	v_add_u32_e32 v173, 0x3000, v182
	v_cvt_pk_bf16_f32 v89, v93, v94
	v_cvt_pk_bf16_f32 v90, v84, v95
	ds_read2_b64 v[92:95], v173 offset0:192 offset1:194
	v_cmp_lt_f32_e32 vcc, s68, v85
	s_waitcnt lgkmcnt(1)
	v_mfma_f32_32x32x16_bf16 v[48:63], v[80:83], v[88:91], v[48:63]
	v_sub_f32_e32 v80, v86, v170
	v_exp_f32_e32 v84, v80
	ds_read2_b64 v[80:83], v183 offset0:132 offset1:134
	v_cndmask_b32_e32 v175, 0, v181, vcc
	v_cmp_lt_f32_e32 vcc, s68, v87
	v_cvt_pk_bf16_f32 v85, v174, v179
	s_mov_b32 s6, 32
	s_waitcnt lgkmcnt(1)
	v_mfma_f32_32x32x16_bf16 v[64:79], v[92:95], v[88:91], v[64:79]
	ds_read2_b64 v[88:91], v173 offset0:196 offset1:198
	v_cndmask_b32_e32 v181, 0, v213, vcc
	v_cmp_lt_f32_e32 vcc, s68, v86
	v_cvt_pk_bf16_f32 v86, v180, v175
	s_nop 0
	v_cndmask_b32_e32 v92, 0, v84, vcc
	v_cvt_pk_bf16_f32 v84, v176, v177
	v_cvt_pk_bf16_f32 v87, v181, v92
	s_andn2_b64 vcc, exec, s[4:5]
	s_mov_b64 s[4:5], 0
	s_waitcnt lgkmcnt(1)
	v_mfma_f32_32x32x16_bf16 v[48:63], v[80:83], v[84:87], v[48:63]
	v_add_f32_e32 v80, v174, v178
	v_add_f32_e32 v80, v179, v80
	v_add_f32_e32 v80, v180, v80
	v_add_f32_e32 v80, v175, v80
	v_add_f32_e32 v80, v181, v80
	v_add_f32_e32 v81, v92, v80
	v_fmac_f32_e32 v81, v172, v0
	s_waitcnt lgkmcnt(0)
	v_mfma_f32_32x32x16_bf16 v[64:79], v[88:91], v[84:87], v[64:79]
	s_cbranch_vccz .LBB0_307
	v_mov_b32_e32 v172, v81
	s_lshl_b32 s7, s12, 6
	s_add_i32 s7, s7, 1
	s_cmp_gt_i32 s7, s8
	s_cbranch_scc1 .Lnsw1_edgeback
	s_branch .LBB0_303
